# speedup vs baseline: 1.0086x; 1.0086x over previous
; #define PG8_STAGE(bufoff, gbase, voff) do { _Pragma("unroll") for (int _i = 0; _i < 2; ++_i) \
;         __builtin_amdgcn_global_load_lds((const unsigned*)((const char*)(gbase) + (voff)[_i]), (PG8_LAS unsigned*)(lds + (bufoff) + ldsw + _i * 8192), 16, 0, 0); } while (0)
; #define PG8_LDA(dst, b, h) do { _Pragma("unroll") for (int m = 0; m < 4; ++m) _Pragma("unroll") for (int k = 0; k < 2; ++k) dst[m][k] = *(const PG8_LAS bf16x8*)(lds + PG8_SA(b, h) + aoff + m * 2048 + k * 1024); } while (0)
; #define PG8_LDB(dst, b, h) do { _Pragma("unroll") for (int n = 0; n < 2; ++n) _Pragma("unroll") for (int k = 0; k < 2; ++k) dst[n][k] = *(const PG8_LAS bf16x8*)(lds + PG8_SB(b, h) + boff + n * 2048 + k * 1024); } while (0)
; #define PG8_MMA(ai, bj, At, Bt) do { __builtin_amdgcn_s_setprio(1); _Pragma("unroll") for (int m = 0; m < 4; ++m) _Pragma("unroll") for (int n = 0; n < 2; ++n) _Pragma("unroll") for (int k = 0; k < 2; ++k) \
;         acc[ai][bj][m][n] = __builtin_amdgcn_mfma_f32_16x16x32_bf16(Bt[n][k], At[m][k], acc[ai][bj][m][n], 0, 0, 0); __builtin_amdgcn_s_setprio(0); } while (0)
; #define PG8_WAIT_L(n) asm volatile("s_waitcnt lgkmcnt(" #n ")" ::: "memory")
; #define PG8_BAR __builtin_amdgcn_s_barrier()
; #define PG8_SCHED __builtin_amdgcn_sched_barrier(0)
; template <class Epi, class Sched>
; __device__ __forceinline__ void gemm_phase(PG8_LAS unsigned char* lds, const Gemm g, const Sched& S, const Epi& E) {
;     ...
;             const bool last = (t == nt - 2);
;             const char* a1 = cA + (size_t)(t + 1) * kstep;
;             const char* a2 = last ? nA : cA + (size_t)(t + 2) * kstep; const char* b2 = last ? nB : cB + (size_t)(t + 2) * kstep;
;             const char* a3 = a2 + kstep; const char* b3 = b2 + kstep;
;             if (last && has_next) S.a_ready(nxt);
;             PG8_LDB(B0, 0, 0); PG8_SCHED; PG8_LDA(At, 0, 0); PG8_STAGE(PG8_SA(1, 1), a1 + hstep, voffA);
;             PG8_WAIT_L(8); PG8_BAR; PG8_WAIT_L(0); PG8_MMA(0, 0, At, B0); PG8_BAR; PG8_SCHED;
;             PG8_LDB(B1, 0, 1); PG8_STAGE(PG8_SB(0, 0), b2, voffB);
;             PG8_BAR; PG8_WAIT_L(0); PG8_MMA(0, 1, At, B1); PG8_BAR;
;             PG8_LDA(At, 0, 1); PG8_STAGE(PG8_SA(0, 0), a2, voffA);
;             PG8_BAR; PG8_WAIT_L(0); PG8_MMA(1, 0, At, B0); PG8_BAR; PG8_SCHED;
.LBB0_120:
	s_add_u32 s4, s10, 0xfff80080
	s_addc_u32 s5, s11, -1
	s_add_i32 s82, 0, 0x10000
	v_add_u32_e32 v148, s82, v154
	ds_read_b128 v[144:147], v148
	ds_read_b128 v[158:161], v148 offset:1024
	ds_read_b128 v[162:165], v148 offset:2048
	ds_read_b128 v[176:179], v148 offset:3072
	s_cmp_eq_u32 s81, 28
	s_cselect_b32 s39, s29, s5
	s_cselect_b32 s38, s73, s4
	s_cselect_b32 s37, s27, s80
	s_cselect_b32 s36, s78, s79
	v_lshl_add_u64 v[148:149], s[10:11], 0, v[140:141]
	s_add_i32 m0, s62, 0xc000
	ds_read_b128 v[180:183], v156
	ds_read_b128 v[184:187], v156 offset:1024
	ds_read_b128 v[188:191], v156 offset:2048
	ds_read_b128 v[192:195], v156 offset:3072
	ds_read_b128 v[196:199], v156 offset:4096
	ds_read_b128 v[200:203], v156 offset:5120
	ds_read_b128 v[204:207], v156 offset:6144
	ds_read_b128 v[208:211], v156 offset:7168
	global_load_lds_dwordx4 v[148:149], off
	v_lshl_add_u64 v[148:149], s[10:11], 0, v[142:143]
	s_add_i32 m0, s62, 0xe000
	s_nop 0
	global_load_lds_dwordx4 v[148:149], off
	s_waitcnt lgkmcnt(8)
	s_barrier
	s_waitcnt lgkmcnt(0)
	s_setprio 1
	s_waitcnt lgkmcnt(0)
	v_mfma_f32_16x16x32_bf16 v[124:127], v[144:147], v[180:183], v[124:127]
	v_mfma_f32_16x16x32_bf16 v[120:123], v[162:165], v[180:183], v[120:123]
	v_mfma_f32_16x16x32_bf16 v[108:111], v[144:147], v[188:191], v[108:111]
	v_mfma_f32_16x16x32_bf16 v[104:107], v[162:165], v[188:191], v[104:107]
	v_mfma_f32_16x16x32_bf16 v[92:95], v[144:147], v[196:199], v[92:95]
	v_mfma_f32_16x16x32_bf16 v[88:91], v[162:165], v[196:199], v[88:91]
	v_mfma_f32_16x16x32_bf16 v[76:79], v[144:147], v[204:207], v[76:79]
	v_mfma_f32_16x16x32_bf16 v[72:75], v[162:165], v[204:207], v[72:75]
	v_mfma_f32_16x16x32_bf16 v[124:127], v[158:161], v[184:187], v[124:127]
	v_mfma_f32_16x16x32_bf16 v[120:123], v[176:179], v[184:187], v[120:123]
	v_mfma_f32_16x16x32_bf16 v[108:111], v[158:161], v[192:195], v[108:111]
	v_mfma_f32_16x16x32_bf16 v[104:107], v[176:179], v[192:195], v[104:107]
	v_mfma_f32_16x16x32_bf16 v[92:95], v[158:161], v[200:203], v[92:95]
	v_mfma_f32_16x16x32_bf16 v[88:91], v[176:179], v[200:203], v[88:91]
	v_mfma_f32_16x16x32_bf16 v[76:79], v[158:161], v[208:211], v[76:79]
	v_mfma_f32_16x16x32_bf16 v[72:75], v[176:179], v[208:211], v[72:75]
	s_setprio 0
	s_barrier
	s_add_i32 s83, 0, 0x14000
	v_add_u32_e32 v148, s83, v154
	s_add_i32 s4, s82, s61
	ds_read_b128 v[212:215], v148
	ds_read_b128 v[216:219], v148 offset:1024
	ds_read_b128 v[220:223], v148 offset:2048
	ds_read_b128 v[224:227], v148 offset:3072
	v_lshl_add_u64 v[148:149], s[36:37], 0, v[128:129]
	s_mov_b32 m0, s4
	v_lshl_add_u64 v[228:229], s[36:37], 0, v[134:135]
	global_load_lds_dwordx4 v[148:149], off
	s_add_i32 m0, s4, 0x2000
	s_nop 0
	global_load_lds_dwordx4 v[228:229], off
	s_barrier
	s_waitcnt lgkmcnt(0)
	s_setprio 1
	s_waitcnt lgkmcnt(0)
	v_mfma_f32_16x16x32_bf16 v[116:119], v[212:215], v[180:183], v[116:119]
	v_mfma_f32_16x16x32_bf16 v[112:115], v[220:223], v[180:183], v[112:115]
	v_mfma_f32_16x16x32_bf16 v[100:103], v[212:215], v[188:191], v[100:103]
	v_mfma_f32_16x16x32_bf16 v[96:99], v[220:223], v[188:191], v[96:99]
	v_mfma_f32_16x16x32_bf16 v[84:87], v[212:215], v[196:199], v[84:87]
	v_mfma_f32_16x16x32_bf16 v[80:83], v[220:223], v[196:199], v[80:83]
	v_mfma_f32_16x16x32_bf16 v[68:71], v[212:215], v[204:207], v[68:71]
	v_mfma_f32_16x16x32_bf16 v[64:67], v[220:223], v[204:207], v[64:67]
	v_mfma_f32_16x16x32_bf16 v[116:119], v[216:219], v[184:187], v[116:119]
	v_mfma_f32_16x16x32_bf16 v[112:115], v[224:227], v[184:187], v[112:115]
	v_mfma_f32_16x16x32_bf16 v[100:103], v[216:219], v[192:195], v[100:103]
	v_mfma_f32_16x16x32_bf16 v[96:99], v[224:227], v[192:195], v[96:99]
	v_mfma_f32_16x16x32_bf16 v[84:87], v[216:219], v[200:203], v[84:87]
	v_mfma_f32_16x16x32_bf16 v[80:83], v[224:227], v[200:203], v[80:83]
	v_mfma_f32_16x16x32_bf16 v[68:71], v[216:219], v[208:211], v[68:71]
	v_mfma_f32_16x16x32_bf16 v[64:67], v[224:227], v[208:211], v[64:67]
	s_setprio 0
	s_mov_b32 m0, s62
	v_lshl_add_u64 v[230:231], s[38:39], 0, v[138:139]
	s_barrier
	ds_read_b128 v[180:183], v156 offset:16384
	ds_read_b128 v[184:187], v156 offset:17408
	ds_read_b128 v[188:191], v156 offset:18432
	ds_read_b128 v[192:195], v156 offset:19456
	ds_read_b128 v[196:199], v156 offset:20480
	ds_read_b128 v[200:203], v156 offset:21504
	ds_read_b128 v[204:207], v156 offset:22528
	ds_read_b128 v[208:211], v156 offset:23552
	global_load_lds_dwordx4 v[230:231], off
	v_lshl_add_u64 v[232:233], s[38:39], 0, v[136:137]
	s_mov_b32 m0, s63
	s_nop 0
	global_load_lds_dwordx4 v[232:233], off
	s_barrier
	s_waitcnt lgkmcnt(0)
	s_setprio 1
	s_waitcnt lgkmcnt(0)
	v_mfma_f32_16x16x32_bf16 v[60:63], v[144:147], v[180:183], v[60:63]
	v_mfma_f32_16x16x32_bf16 v[56:59], v[162:165], v[180:183], v[56:59]
	v_mfma_f32_16x16x32_bf16 v[44:47], v[144:147], v[188:191], v[44:47]
	v_mfma_f32_16x16x32_bf16 v[40:43], v[162:165], v[188:191], v[40:43]
	v_mfma_f32_16x16x32_bf16 v[28:31], v[144:147], v[196:199], v[28:31]
	v_mfma_f32_16x16x32_bf16 v[24:27], v[162:165], v[196:199], v[24:27]
	v_mfma_f32_16x16x32_bf16 v[12:15], v[144:147], v[204:207], v[12:15]
	v_mfma_f32_16x16x32_bf16 v[8:11], v[162:165], v[204:207], v[8:11]
	v_mfma_f32_16x16x32_bf16 v[60:63], v[158:161], v[184:187], v[60:63]
	v_mfma_f32_16x16x32_bf16 v[56:59], v[176:179], v[184:187], v[56:59]
	v_mfma_f32_16x16x32_bf16 v[44:47], v[158:161], v[192:195], v[44:47]
	v_mfma_f32_16x16x32_bf16 v[40:43], v[176:179], v[192:195], v[40:43]
	v_mfma_f32_16x16x32_bf16 v[28:31], v[158:161], v[200:203], v[28:31]
	v_mfma_f32_16x16x32_bf16 v[24:27], v[176:179], v[200:203], v[24:27]
	v_mfma_f32_16x16x32_bf16 v[12:15], v[158:161], v[208:211], v[12:15]
	v_mfma_f32_16x16x32_bf16 v[8:11], v[176:179], v[208:211], v[8:11]
	s_setprio 0
	s_barrier
; #define PG8_STAGE(bufoff, gbase, voff) do { _Pragma("unroll") for (int _i = 0; _i < 2; ++_i) \
;         __builtin_amdgcn_global_load_lds((const unsigned*)((const char*)(gbase) + (voff)[_i]), (PG8_LAS unsigned*)(lds + (bufoff) + ldsw + _i * 8192), 16, 0, 0); } while (0)
; #define PG8_LDA(dst, b, h) do { _Pragma("unroll") for (int m = 0; m < 4; ++m) _Pragma("unroll") for (int k = 0; k < 2; ++k) dst[m][k] = *(const PG8_LAS bf16x8*)(lds + PG8_SA(b, h) + aoff + m * 2048 + k * 1024); } while (0)
; #define PG8_LDB(dst, b, h) do { _Pragma("unroll") for (int n = 0; n < 2; ++n) _Pragma("unroll") for (int k = 0; k < 2; ++k) dst[n][k] = *(const PG8_LAS bf16x8*)(lds + PG8_SB(b, h) + boff + n * 2048 + k * 1024); } while (0)
; #define PG8_MMA(ai, bj, At, Bt) do { __builtin_amdgcn_s_setprio(1); _Pragma("unroll") for (int m = 0; m < 4; ++m) _Pragma("unroll") for (int n = 0; n < 2; ++n) _Pragma("unroll") for (int k = 0; k < 2; ++k) \
;         acc[ai][bj][m][n] = __builtin_amdgcn_mfma_f32_16x16x32_bf16(Bt[n][k], At[m][k], acc[ai][bj][m][n], 0, 0, 0); __builtin_amdgcn_s_setprio(0); } while (0)
; #define PG8_WAIT_V(n) asm volatile("s_waitcnt vmcnt(" #n ")" ::: "memory")
; #define PG8_WAIT_L(n) asm volatile("s_waitcnt lgkmcnt(" #n ")" ::: "memory")
; #define PG8_BAR __builtin_amdgcn_s_barrier()
; #define PG8_SCHED __builtin_amdgcn_sched_barrier(0)
; template <class Epi, class Sched>
; __device__ __forceinline__ void gemm_phase(PG8_LAS unsigned char* lds, const Gemm g, const Sched& S, const Epi& E) {
;     ...
;             PG8_STAGE(PG8_SB(0, 1), b2 + hstep, voffB);
;             PG8_WAIT_V(6); PG8_BAR; PG8_MMA(1, 1, At, B1); PG8_BAR;
;             PG8_LDB(B0, 1, 0); PG8_SCHED; PG8_LDA(At, 1, 0); PG8_STAGE(PG8_SA(0, 1), a2 + hstep, voffA);
;             PG8_WAIT_L(8); PG8_BAR; PG8_WAIT_L(0); PG8_MMA(0, 0, At, B0); PG8_BAR; PG8_SCHED;
;             PG8_LDB(B1, 1, 1); PG8_STAGE(PG8_SB(1, 0), b3, voffB);
;             PG8_BAR; PG8_WAIT_L(0); PG8_MMA(0, 1, At, B1); PG8_BAR;
;             PG8_LDA(At, 1, 1); PG8_STAGE(PG8_SA(1, 0), a3, voffA);
;             PG8_BAR; PG8_WAIT_L(0); PG8_MMA(1, 0, At, B0); PG8_BAR; PG8_SCHED;
	s_add_u32 s4, s36, 0x80000
	s_addc_u32 s5, s37, 0
	s_add_i32 s82, s83, s61
	v_lshl_add_u64 v[144:145], s[4:5], 0, v[128:129]
	s_mov_b32 m0, s82
	s_nop 0
	global_load_lds_dwordx4 v[144:145], off
	v_lshl_add_u64 v[144:145], s[4:5], 0, v[134:135]
	s_add_i32 m0, s82, 0x2000
	s_nop 0
	global_load_lds_dwordx4 v[144:145], off
	s_waitcnt vmcnt(6)
	s_barrier
	s_setprio 1
	v_mfma_f32_16x16x32_bf16 v[52:55], v[212:215], v[180:183], v[52:55]
	v_mfma_f32_16x16x32_bf16 v[48:51], v[220:223], v[180:183], v[48:51]
	v_mfma_f32_16x16x32_bf16 v[36:39], v[212:215], v[188:191], v[36:39]
	v_mfma_f32_16x16x32_bf16 v[32:35], v[220:223], v[188:191], v[32:35]
	v_mfma_f32_16x16x32_bf16 v[20:23], v[212:215], v[196:199], v[20:23]
	v_mfma_f32_16x16x32_bf16 v[16:19], v[220:223], v[196:199], v[16:19]
	v_mfma_f32_16x16x32_bf16 v[4:7], v[212:215], v[204:207], v[4:7]
	v_mfma_f32_16x16x32_bf16 v[0:3], v[220:223], v[204:207], v[0:3]
	v_mfma_f32_16x16x32_bf16 v[52:55], v[216:219], v[184:187], v[52:55]
	v_mfma_f32_16x16x32_bf16 v[48:51], v[224:227], v[184:187], v[48:51]
	v_mfma_f32_16x16x32_bf16 v[36:39], v[216:219], v[192:195], v[36:39]
	v_mfma_f32_16x16x32_bf16 v[32:35], v[224:227], v[192:195], v[32:35]
	v_mfma_f32_16x16x32_bf16 v[20:23], v[216:219], v[200:203], v[20:23]
	v_mfma_f32_16x16x32_bf16 v[16:19], v[224:227], v[200:203], v[16:19]
	v_mfma_f32_16x16x32_bf16 v[4:7], v[216:219], v[208:211], v[4:7]
	v_mfma_f32_16x16x32_bf16 v[0:3], v[224:227], v[208:211], v[0:3]
	s_setprio 0
	s_add_i32 s82, 0, 0x18000
	v_add_u32_e32 v157, s82, v154
	s_barrier
	ds_read_b128 v[144:147], v157
	ds_read_b128 v[158:161], v157 offset:1024
	ds_read_b128 v[162:165], v157 offset:2048
	ds_read_b128 v[176:179], v157 offset:3072
	s_add_u32 s4, s38, 0x80000
	s_addc_u32 s5, s39, 0
	s_mov_b32 m0, s64
	v_lshl_add_u64 v[212:213], s[4:5], 0, v[138:139]
	ds_read_b128 v[180:183], v156 offset:32768
	ds_read_b128 v[184:187], v156 offset:33792
	ds_read_b128 v[188:191], v156 offset:34816
	ds_read_b128 v[192:195], v156 offset:35840
	ds_read_b128 v[196:199], v156 offset:36864
	ds_read_b128 v[200:203], v156 offset:37888
	ds_read_b128 v[204:207], v156 offset:38912
	ds_read_b128 v[208:211], v156 offset:39936
	global_load_lds_dwordx4 v[212:213], off
	v_lshl_add_u64 v[212:213], s[4:5], 0, v[136:137]
	s_mov_b32 m0, s65
	s_nop 0
	global_load_lds_dwordx4 v[212:213], off
	s_waitcnt lgkmcnt(8)
	s_barrier
	s_waitcnt lgkmcnt(0)
	s_setprio 1
	s_waitcnt lgkmcnt(0)
	v_mfma_f32_16x16x32_bf16 v[124:127], v[144:147], v[180:183], v[124:127]
	v_mfma_f32_16x16x32_bf16 v[120:123], v[162:165], v[180:183], v[120:123]
	v_mfma_f32_16x16x32_bf16 v[108:111], v[144:147], v[188:191], v[108:111]
	v_mfma_f32_16x16x32_bf16 v[104:107], v[162:165], v[188:191], v[104:107]
	v_mfma_f32_16x16x32_bf16 v[92:95], v[144:147], v[196:199], v[92:95]
	v_mfma_f32_16x16x32_bf16 v[88:91], v[162:165], v[196:199], v[88:91]
	v_mfma_f32_16x16x32_bf16 v[76:79], v[144:147], v[204:207], v[76:79]
	v_mfma_f32_16x16x32_bf16 v[72:75], v[162:165], v[204:207], v[72:75]
	v_mfma_f32_16x16x32_bf16 v[124:127], v[158:161], v[184:187], v[124:127]
	v_mfma_f32_16x16x32_bf16 v[120:123], v[176:179], v[184:187], v[120:123]
	v_mfma_f32_16x16x32_bf16 v[108:111], v[158:161], v[192:195], v[108:111]
	v_mfma_f32_16x16x32_bf16 v[104:107], v[176:179], v[192:195], v[104:107]
	v_mfma_f32_16x16x32_bf16 v[92:95], v[158:161], v[200:203], v[92:95]
	v_mfma_f32_16x16x32_bf16 v[88:91], v[176:179], v[200:203], v[88:91]
	v_mfma_f32_16x16x32_bf16 v[76:79], v[158:161], v[208:211], v[76:79]
	v_mfma_f32_16x16x32_bf16 v[72:75], v[176:179], v[208:211], v[72:75]
	s_setprio 0
	s_barrier
	s_add_i32 s38, 0, 0x1c000
	s_add_i32 s4, s82, s61
	v_add_u32_e32 v157, s38, v154
	v_lshl_add_u64 v[148:149], v[148:149], 0, s[18:19]
	s_mov_b32 m0, s4
	ds_read_b128 v[212:215], v157
	ds_read_b128 v[216:219], v157 offset:1024
	ds_read_b128 v[220:223], v157 offset:2048
	ds_read_b128 v[224:227], v157 offset:3072
	global_load_lds_dwordx4 v[148:149], off
	v_lshl_add_u64 v[148:149], v[228:229], 0, s[18:19]
	s_add_i32 m0, s4, 0x2000
	s_nop 0
	global_load_lds_dwordx4 v[148:149], off
	s_barrier
	s_waitcnt lgkmcnt(0)
	s_setprio 1
	s_waitcnt lgkmcnt(0)
	v_mfma_f32_16x16x32_bf16 v[116:119], v[212:215], v[180:183], v[116:119]
	v_mfma_f32_16x16x32_bf16 v[112:115], v[220:223], v[180:183], v[112:115]
	v_mfma_f32_16x16x32_bf16 v[100:103], v[212:215], v[188:191], v[100:103]
	v_mfma_f32_16x16x32_bf16 v[96:99], v[220:223], v[188:191], v[96:99]
	v_mfma_f32_16x16x32_bf16 v[84:87], v[212:215], v[196:199], v[84:87]
	v_mfma_f32_16x16x32_bf16 v[80:83], v[220:223], v[196:199], v[80:83]
	v_mfma_f32_16x16x32_bf16 v[68:71], v[212:215], v[204:207], v[68:71]
	v_mfma_f32_16x16x32_bf16 v[64:67], v[220:223], v[204:207], v[64:67]
	v_mfma_f32_16x16x32_bf16 v[116:119], v[216:219], v[184:187], v[116:119]
	v_mfma_f32_16x16x32_bf16 v[112:115], v[224:227], v[184:187], v[112:115]
	v_mfma_f32_16x16x32_bf16 v[100:103], v[216:219], v[192:195], v[100:103]
	v_mfma_f32_16x16x32_bf16 v[96:99], v[224:227], v[192:195], v[96:99]
	v_mfma_f32_16x16x32_bf16 v[84:87], v[216:219], v[200:203], v[84:87]
	v_mfma_f32_16x16x32_bf16 v[80:83], v[224:227], v[200:203], v[80:83]
	v_mfma_f32_16x16x32_bf16 v[68:71], v[216:219], v[208:211], v[68:71]
	v_mfma_f32_16x16x32_bf16 v[64:67], v[224:227], v[208:211], v[64:67]
	s_setprio 0
	s_mov_b32 m0, s66
	v_lshl_add_u64 v[148:149], v[230:231], 0, s[18:19]
	s_barrier
	ds_read_b128 v[180:183], v156 offset:49152
	ds_read_b128 v[184:187], v156 offset:50176
	ds_read_b128 v[188:191], v156 offset:51200
	ds_read_b128 v[192:195], v156 offset:52224
	ds_read_b128 v[196:199], v156 offset:53248
	ds_read_b128 v[200:203], v156 offset:54272
	ds_read_b128 v[204:207], v156 offset:55296
	ds_read_b128 v[208:211], v156 offset:56320
	global_load_lds_dwordx4 v[148:149], off
	v_lshl_add_u64 v[148:149], v[232:233], 0, s[18:19]
	s_mov_b32 m0, s67
	s_nop 0
	global_load_lds_dwordx4 v[148:149], off
	s_barrier
; __device__ __forceinline__ unsigned cvt_pk_bf16(float lo, float hi) { unsigned r; asm volatile("v_cvt_pk_bf16_f32 %0, %1, %2" : "=v"(r) : "v"(lo), "v"(hi)); return r; }
; #define PG8_WAIT_V(n) asm volatile("s_waitcnt vmcnt(" #n ")" ::: "memory")
; #define PG8_WAIT_L(n) asm volatile("s_waitcnt lgkmcnt(" #n ")" ::: "memory")
; template <class Epi, class Sched>
; __device__ __forceinline__ void gemm_phase(PG8_LAS unsigned char* lds, const Gemm g, const Sched& S, const Epi& E) {
;     ...
;             PG8_BAR; PG8_WAIT_L(0); PG8_MMA(1, 0, At, B0); PG8_BAR; PG8_SCHED;
;             PG8_STAGE(PG8_SB(1, 1), b3 + hstep, voffB);
;             PG8_WAIT_V(6); PG8_BAR; PG8_MMA(1, 1, At, B1); PG8_BAR;
;     __device__ __forceinline__ void operator()(const f32x4 (&acc)[2][2][4][2], const pg8::Unit& u, int wr, int wc, int fr, int fq) const {
;         const int row0 = u.pm * 256 + wr * 64 + fr, col0 = u.pn * 256 + wc * 32 + 8 * fq;
;         const bool rot = u.pn < 8; const float ksc = (u.pn >= 4) ? 0.08838834764831845f : 1.0f;
; #pragma unroll
;         for (int ai = 0; ai < 2; ++ai)
; #pragma unroll
;             for (int m = 0; m < 4; ++m) {
;                 const int row = row0 + ai * 128 + m * 16;
;                 bf16_t* rowp = O + (size_t)row * INP + col0;
; #pragma unroll
;                 for (int bj = 0; bj < 2; ++bj) {
;                     f32x4 v0 = acc[ai][bj][m][0], v1 = acc[ai][bj][m][1];
;                     if (rot) {
;                         const int pos = row & (SEQ - 1), j0 = ((col0 + bj * 128) & 127) >> 1;
;                         const f32x4* t = (const f32x4*)(sc + ((size_t)pos * 64 + j0) * 2);
;                         const f32x4 t0 = t[0], t1 = t[1];
;                         f32x4 r0, r1;
;                         r0[0] = v0[0] * t0[0] - v0[1] * t0[1]; r0[1] = v0[0] * t0[1] + v0[1] * t0[0];
;                         r0[2] = v0[2] * t0[2] - v0[3] * t0[3]; r0[3] = v0[2] * t0[3] + v0[3] * t0[2];
;                         r1[0] = v1[0] * t1[0] - v1[1] * t1[1]; r1[1] = v1[0] * t1[1] + v1[1] * t1[0];
;                         r1[2] = v1[2] * t1[2] - v1[3] * t1[3]; r1[3] = v1[2] * t1[3] + v1[3] * t1[2];
;                         v0 = r0 * ksc; v1 = r1 * ksc;
;                     }
;                     u32x4 w; w.x = cvt_pk_bf16(v0[0], v0[1]); w.y = cvt_pk_bf16(v0[2], v0[3]); w.z = cvt_pk_bf16(v1[0], v1[1]); w.w = cvt_pk_bf16(v1[2], v1[3]);
	s_waitcnt lgkmcnt(0)
	s_setprio 1
	s_waitcnt lgkmcnt(0)
	v_mfma_f32_16x16x32_bf16 v[60:63], v[144:147], v[180:183], v[60:63]
	v_mfma_f32_16x16x32_bf16 v[56:59], v[162:165], v[180:183], v[56:59]
	v_mfma_f32_16x16x32_bf16 v[44:47], v[144:147], v[188:191], v[44:47]
	v_mfma_f32_16x16x32_bf16 v[40:43], v[162:165], v[188:191], v[40:43]
	v_mfma_f32_16x16x32_bf16 v[28:31], v[144:147], v[196:199], v[28:31]
	v_mfma_f32_16x16x32_bf16 v[24:27], v[162:165], v[196:199], v[24:27]
	v_mfma_f32_16x16x32_bf16 v[12:15], v[144:147], v[204:207], v[12:15]
	v_mfma_f32_16x16x32_bf16 v[8:11], v[162:165], v[204:207], v[8:11]
	v_mfma_f32_16x16x32_bf16 v[60:63], v[158:161], v[184:187], v[60:63]
	v_mfma_f32_16x16x32_bf16 v[56:59], v[176:179], v[184:187], v[56:59]
	v_mfma_f32_16x16x32_bf16 v[44:47], v[158:161], v[192:195], v[44:47]
	v_mfma_f32_16x16x32_bf16 v[40:43], v[176:179], v[192:195], v[40:43]
	v_mfma_f32_16x16x32_bf16 v[28:31], v[158:161], v[200:203], v[28:31]
	v_mfma_f32_16x16x32_bf16 v[24:27], v[176:179], v[200:203], v[24:27]
	v_mfma_f32_16x16x32_bf16 v[12:15], v[158:161], v[208:211], v[12:15]
	v_mfma_f32_16x16x32_bf16 v[8:11], v[176:179], v[208:211], v[8:11]
	s_setprio 0
	s_barrier
	s_add_u32 s4, s36, 0x80080
	s_addc_u32 s5, s37, 0
	s_add_i32 s36, s38, s61
	v_lshl_add_u64 v[144:145], s[4:5], 0, v[128:129]
	s_mov_b32 m0, s36
	s_nop 0
	global_load_lds_dwordx4 v[144:145], off
	v_lshl_add_u64 v[144:145], s[4:5], 0, v[134:135]
	s_add_i32 m0, s36, 0x2000
	s_nop 0
	global_load_lds_dwordx4 v[144:145], off
	s_waitcnt vmcnt(6)
	s_barrier
	s_setprio 1
	v_mfma_f32_16x16x32_bf16 v[52:55], v[212:215], v[180:183], v[52:55]
	v_mfma_f32_16x16x32_bf16 v[48:51], v[220:223], v[180:183], v[48:51]
	v_mfma_f32_16x16x32_bf16 v[36:39], v[212:215], v[188:191], v[36:39]
	v_mfma_f32_16x16x32_bf16 v[32:35], v[220:223], v[188:191], v[32:35]
	v_mfma_f32_16x16x32_bf16 v[20:23], v[212:215], v[196:199], v[20:23]
	v_mfma_f32_16x16x32_bf16 v[16:19], v[220:223], v[196:199], v[16:19]
	v_mfma_f32_16x16x32_bf16 v[4:7], v[212:215], v[204:207], v[4:7]
	v_mfma_f32_16x16x32_bf16 v[0:3], v[220:223], v[204:207], v[0:3]
	v_mfma_f32_16x16x32_bf16 v[52:55], v[216:219], v[184:187], v[52:55]
	v_mfma_f32_16x16x32_bf16 v[48:51], v[224:227], v[184:187], v[48:51]
	v_mfma_f32_16x16x32_bf16 v[36:39], v[216:219], v[192:195], v[36:39]
	v_mfma_f32_16x16x32_bf16 v[32:35], v[224:227], v[192:195], v[32:35]
	v_mfma_f32_16x16x32_bf16 v[20:23], v[216:219], v[200:203], v[20:23]
	v_mfma_f32_16x16x32_bf16 v[16:19], v[224:227], v[200:203], v[16:19]
	v_mfma_f32_16x16x32_bf16 v[4:7], v[216:219], v[208:211], v[4:7]
	v_mfma_f32_16x16x32_bf16 v[0:3], v[224:227], v[208:211], v[0:3]
	s_setprio 0
	s_add_i32 s81, s81, 2
	s_add_u32 s10, s10, 0x100
	s_addc_u32 s11, s11, 0
	s_add_u32 s79, s79, 0x100
	s_addc_u32 s80, s80, 0
	s_cmp_gt_u32 s81, 29
	s_barrier
	s_cbranch_scc0 .LBB0_120
	s_lshl_b32 s10, s69, 8
	s_cmp_lt_i32 s69, 8
	v_lshl_add_u32 v157, s71, 8, v153
	s_cselect_b64 s[36:37], -1, 0
	s_cmp_gt_i32 s69, 3
	s_cselect_b64 vcc, -1, 0
	v_bitop3_b32 v158, s10, v152, v155 bitop3:0xc8
	v_lshlrev_b32_e32 v146, 7, v157
	v_cndmask_b32_e32 v144, 1.0, v151, vcc
	v_and_or_b32 v146, v146, s49, v158
	s_cmp_gt_i32 s69, 7
	v_mov_b32_e32 v145, v144
	v_lshlrev_b32_e32 v159, 2, v146
	s_cbranch_scc1 .LBB0_123
	s_mov_b32 s98, 0xfff80
	v_mov_b32_e32 v226, v157
	v_lshlrev_b32_e32 v226, 7, v226
	v_and_or_b32 v226, v226, s98, v158
	v_lshlrev_b32_e32 v218, 2, v226
	v_add_u32_e32 v226, 16, v157
	v_lshlrev_b32_e32 v226, 7, v226
	v_and_or_b32 v226, v226, s98, v158
	v_lshlrev_b32_e32 v219, 2, v226
	v_add_u32_e32 v226, 32, v157
	v_lshlrev_b32_e32 v226, 7, v226
	v_and_or_b32 v226, v226, s98, v158
	v_lshlrev_b32_e32 v220, 2, v226
	v_add_u32_e32 v226, 48, v157
	v_lshlrev_b32_e32 v226, 7, v226
	v_and_or_b32 v226, v226, s98, v158
	v_lshlrev_b32_e32 v221, 2, v226
	v_add_u32_e32 v226, 128, v157
	v_lshlrev_b32_e32 v226, 7, v226
	v_and_or_b32 v226, v226, s98, v158
	v_lshlrev_b32_e32 v222, 2, v226
	v_add_u32_e32 v226, 144, v157
	v_lshlrev_b32_e32 v226, 7, v226
	v_and_or_b32 v226, v226, s98, v158
	v_lshlrev_b32_e32 v223, 2, v226
	v_add_u32_e32 v226, 160, v157
	v_lshlrev_b32_e32 v226, 7, v226
	v_and_or_b32 v226, v226, s98, v158
	v_lshlrev_b32_e32 v224, 2, v226
	v_add_u32_e32 v226, 176, v157
	v_lshlrev_b32_e32 v226, 7, v226
	v_and_or_b32 v226, v226, s98, v158
	v_lshlrev_b32_e32 v225, 2, v226
	global_load_dwordx4 v[186:189], v218, s[24:25]
	global_load_dwordx4 v[190:193], v218, s[24:25] offset:16
	global_load_dwordx4 v[194:197], v219, s[24:25]
	global_load_dwordx4 v[198:201], v219, s[24:25] offset:16
	global_load_dwordx4 v[202:205], v220, s[24:25]
	global_load_dwordx4 v[206:209], v220, s[24:25] offset:16
	global_load_dwordx4 v[210:213], v221, s[24:25]
	global_load_dwordx4 v[214:217], v221, s[24:25] offset:16
	v_mov_b32_e32 v164, v127
	v_mov_b32_e32 v176, v123
	v_mov_b32_e32 v178, v144
	v_mov_b32_e32 v179, v144
	s_waitcnt vmcnt(6)
	v_mov_b64_e32 v[146:147], v[186:187]
	v_mov_b64_e32 v[148:149], v[188:189]
	v_mov_b64_e32 v[160:161], v[190:191]
	v_mov_b64_e32 v[162:163], v[192:193]
	v_pk_mul_f32 v[180:181], v[124:125], v[146:147] op_sel:[1,1] op_sel_hi:[1,0]
	v_pk_mul_f32 v[164:165], v[164:165], v[148:149] op_sel:[0,1] op_sel_hi:[0,0]
	v_pk_mul_f32 v[182:183], v[120:121], v[160:161] op_sel:[1,1] op_sel_hi:[1,0]
	v_pk_mul_f32 v[176:177], v[176:177], v[162:163] op_sel:[0,1] op_sel_hi:[0,0]
	v_pk_fma_f32 v[184:185], v[124:125], v[146:147], v[180:181] op_sel_hi:[0,1,1] neg_lo:[0,0,1] neg_hi:[0,0,1]
	v_pk_fma_f32 v[124:125], v[124:125], v[146:147], v[180:181] op_sel_hi:[0,1,1]
	v_pk_fma_f32 v[146:147], v[126:127], v[148:149], v[164:165] op_sel_hi:[0,1,1] neg_lo:[0,0,1] neg_hi:[0,0,1]
	v_pk_fma_f32 v[126:127], v[126:127], v[148:149], v[164:165] op_sel_hi:[0,1,1]
	v_pk_fma_f32 v[148:149], v[120:121], v[160:161], v[182:183] op_sel_hi:[0,1,1] neg_lo:[0,0,1] neg_hi:[0,0,1]
	v_pk_fma_f32 v[120:121], v[120:121], v[160:161], v[182:183] op_sel_hi:[0,1,1]
	v_pk_fma_f32 v[160:161], v[122:123], v[162:163], v[176:177] op_sel_hi:[0,1,1] neg_lo:[0,0,1] neg_hi:[0,0,1]
	v_pk_fma_f32 v[122:123], v[122:123], v[162:163], v[176:177] op_sel_hi:[0,1,1]
	v_mov_b32_e32 v147, v127
	v_mov_b32_e32 v185, v125
	v_mov_b32_e32 v161, v123
	v_mov_b32_e32 v149, v121
	v_pk_mul_f32 v[126:127], v[178:179], v[146:147]
	v_pk_mul_f32 v[124:125], v[144:145], v[184:185]
	v_pk_mul_f32 v[122:123], v[178:179], v[160:161]
	v_pk_mul_f32 v[120:121], v[144:145], v[148:149]
; __device__ __forceinline__ unsigned cvt_pk_bf16(float lo, float hi) { unsigned r; asm volatile("v_cvt_pk_bf16_f32 %0, %1, %2" : "=v"(r) : "v"(lo), "v"(hi)); return r; }
;     __device__ __forceinline__ void operator()(const f32x4 (&acc)[2][2][4][2], const pg8::Unit& u, int wr, int wc, int fr, int fq) const {
;     ...
;         for (int ai = 0; ai < 2; ++ai)
; #pragma unroll
;             for (int m = 0; m < 4; ++m) {
;                 const int row = row0 + ai * 128 + m * 16;
;                 bf16_t* rowp = O + (size_t)row * INP + col0;
; #pragma unroll
;                 for (int bj = 0; bj < 2; ++bj) {
;                     f32x4 v0 = acc[ai][bj][m][0], v1 = acc[ai][bj][m][1];
;                     if (rot) {
;                         const int pos = row & (SEQ - 1), j0 = ((col0 + bj * 128) & 127) >> 1;
;                         const f32x4* t = (const f32x4*)(sc + ((size_t)pos * 64 + j0) * 2);
;                         const f32x4 t0 = t[0], t1 = t[1];
;                         f32x4 r0, r1;
;                         r0[0] = v0[0] * t0[0] - v0[1] * t0[1]; r0[1] = v0[0] * t0[1] + v0[1] * t0[0];
;                         r0[2] = v0[2] * t0[2] - v0[3] * t0[3]; r0[3] = v0[2] * t0[3] + v0[3] * t0[2];
;                         r1[0] = v1[0] * t1[0] - v1[1] * t1[1]; r1[1] = v1[0] * t1[1] + v1[1] * t1[0];
;                         r1[2] = v1[2] * t1[2] - v1[3] * t1[3]; r1[3] = v1[2] * t1[3] + v1[3] * t1[2];
;                         v0 = r0 * ksc; v1 = r1 * ksc;
;                     }
;                     u32x4 w; w.x = cvt_pk_bf16(v0[0], v0[1]); w.y = cvt_pk_bf16(v0[2], v0[3]); w.z = cvt_pk_bf16(v1[0], v1[1]); w.w = cvt_pk_bf16(v1[2], v1[3]);
;                     *(u32x4*)(rowp + bj * 128) = w;
.LBB0_123:
	v_or_b32_e32 v146, s10, v155
	v_mov_b64_e32 v[148:149], s[22:23]
	v_ashrrev_i32_e32 v147, 31, v146
	v_mad_i64_i32 v[148:149], s[4:5], v157, s54, v[148:149]
	v_cvt_pk_bf16_f32 v124, v124, v125
	v_cvt_pk_bf16_f32 v125, v126, v127
	v_cvt_pk_bf16_f32 v126, v120, v121
	v_cndmask_b32_e64 v120, 0, 1, s[36:37]
	v_lshl_add_u64 v[148:149], v[146:147], 1, v[148:149]
	v_cmp_ne_u32_e64 s[10:11], 1, v120
	s_andn2_b64 vcc, exec, s[36:37]
	v_cvt_pk_bf16_f32 v127, v122, v123
	global_store_dwordx4 v[148:149], v[124:127], off
	s_cbranch_vccnz .LBB0_125
	v_mov_b32_e32 v160, v119
	v_mov_b32_e32 v162, v115
	v_mov_b32_e32 v164, v144
	v_mov_b32_e32 v165, v144
	v_mov_b64_e32 v[120:121], v[186:187]
	v_mov_b64_e32 v[122:123], v[188:189]
	v_mov_b64_e32 v[124:125], v[190:191]
	v_mov_b64_e32 v[126:127], v[192:193]
	v_pk_mul_f32 v[176:177], v[116:117], v[120:121] op_sel:[1,1] op_sel_hi:[1,0]
	v_pk_mul_f32 v[160:161], v[160:161], v[122:123] op_sel:[0,1] op_sel_hi:[0,0]
	v_pk_mul_f32 v[178:179], v[112:113], v[124:125] op_sel:[1,1] op_sel_hi:[1,0]
	v_pk_mul_f32 v[162:163], v[162:163], v[126:127] op_sel:[0,1] op_sel_hi:[0,0]
	v_pk_fma_f32 v[180:181], v[116:117], v[120:121], v[176:177] op_sel_hi:[0,1,1] neg_lo:[0,0,1] neg_hi:[0,0,1]
	v_pk_fma_f32 v[116:117], v[116:117], v[120:121], v[176:177] op_sel_hi:[0,1,1]
	v_pk_fma_f32 v[120:121], v[118:119], v[122:123], v[160:161] op_sel_hi:[0,1,1] neg_lo:[0,0,1] neg_hi:[0,0,1]
	v_pk_fma_f32 v[118:119], v[118:119], v[122:123], v[160:161] op_sel_hi:[0,1,1]
	v_pk_fma_f32 v[122:123], v[112:113], v[124:125], v[178:179] op_sel_hi:[0,1,1] neg_lo:[0,0,1] neg_hi:[0,0,1]
	v_pk_fma_f32 v[112:113], v[112:113], v[124:125], v[178:179] op_sel_hi:[0,1,1]
	v_pk_fma_f32 v[124:125], v[114:115], v[126:127], v[162:163] op_sel_hi:[0,1,1] neg_lo:[0,0,1] neg_hi:[0,0,1]
	v_pk_fma_f32 v[114:115], v[114:115], v[126:127], v[162:163] op_sel_hi:[0,1,1]
	v_mov_b32_e32 v121, v119
	v_mov_b32_e32 v181, v117
	v_mov_b32_e32 v125, v115
	v_mov_b32_e32 v123, v113
	v_pk_mul_f32 v[118:119], v[164:165], v[120:121]
	v_pk_mul_f32 v[116:117], v[144:145], v[180:181]
	v_pk_mul_f32 v[114:115], v[164:165], v[124:125]
	v_pk_mul_f32 v[112:113], v[144:145], v[122:123]
.LBB0_125:
	v_cvt_pk_bf16_f32 v116, v116, v117
	v_cvt_pk_bf16_f32 v117, v118, v119
	s_nop 0
	v_cvt_pk_bf16_f32 v118, v112, v113
	v_or_b32_e32 v112, 16, v157
	v_lshlrev_b32_e32 v113, 7, v112
	v_and_or_b32 v113, v113, s55, v158
	v_cvt_pk_bf16_f32 v119, v114, v115
	s_and_b64 vcc, exec, s[10:11]
	v_lshlrev_b32_e32 v114, 2, v113
	global_store_dwordx4 v[148:149], v[116:119], off offset:256
	s_cbranch_vccnz .LBB0_127
	global_load_dwordx4 v[186:189], v222, s[24:25]
	global_load_dwordx4 v[190:193], v222, s[24:25] offset:16
	v_mov_b32_e32 v124, v111
	v_mov_b32_e32 v126, v107
	v_mov_b32_e32 v148, v144
	v_mov_b32_e32 v149, v144
	s_waitcnt vmcnt(8)
	v_mov_b64_e32 v[116:117], v[194:195]
	v_mov_b64_e32 v[118:119], v[196:197]
	v_mov_b64_e32 v[120:121], v[198:199]
	v_mov_b64_e32 v[122:123], v[200:201]
	v_pk_mul_f32 v[160:161], v[108:109], v[116:117] op_sel:[1,1] op_sel_hi:[1,0]
	v_pk_mul_f32 v[124:125], v[124:125], v[118:119] op_sel:[0,1] op_sel_hi:[0,0]
	v_pk_mul_f32 v[162:163], v[104:105], v[120:121] op_sel:[1,1] op_sel_hi:[1,0]
	v_pk_mul_f32 v[126:127], v[126:127], v[122:123] op_sel:[0,1] op_sel_hi:[0,0]
	v_pk_fma_f32 v[164:165], v[108:109], v[116:117], v[160:161] op_sel_hi:[0,1,1] neg_lo:[0,0,1] neg_hi:[0,0,1]
	v_pk_fma_f32 v[108:109], v[108:109], v[116:117], v[160:161] op_sel_hi:[0,1,1]
	v_pk_fma_f32 v[116:117], v[110:111], v[118:119], v[124:125] op_sel_hi:[0,1,1] neg_lo:[0,0,1] neg_hi:[0,0,1]
	v_pk_fma_f32 v[110:111], v[110:111], v[118:119], v[124:125] op_sel_hi:[0,1,1]
	v_pk_fma_f32 v[118:119], v[104:105], v[120:121], v[162:163] op_sel_hi:[0,1,1] neg_lo:[0,0,1] neg_hi:[0,0,1]
	v_pk_fma_f32 v[104:105], v[104:105], v[120:121], v[162:163] op_sel_hi:[0,1,1]
	v_pk_fma_f32 v[120:121], v[106:107], v[122:123], v[126:127] op_sel_hi:[0,1,1] neg_lo:[0,0,1] neg_hi:[0,0,1]
	v_pk_fma_f32 v[106:107], v[106:107], v[122:123], v[126:127] op_sel_hi:[0,1,1]
	v_mov_b32_e32 v117, v111
	v_mov_b32_e32 v165, v109
	v_mov_b32_e32 v121, v107
	v_mov_b32_e32 v119, v105
	v_pk_mul_f32 v[110:111], v[148:149], v[116:117]
	v_pk_mul_f32 v[108:109], v[144:145], v[164:165]
	v_pk_mul_f32 v[106:107], v[148:149], v[120:121]
	v_pk_mul_f32 v[104:105], v[144:145], v[118:119]
.LBB0_127:
	s_nop 0
	v_mov_b64_e32 v[116:117], s[22:23]
	v_mad_i64_i32 v[112:113], s[4:5], v112, s54, v[116:117]
	v_lshl_add_u64 v[112:113], v[146:147], 1, v[112:113]
	s_and_b64 vcc, exec, s[10:11]
	v_cvt_pk_bf16_f32 v108, v108, v109
	v_cvt_pk_bf16_f32 v109, v110, v111
	v_cvt_pk_bf16_f32 v110, v104, v105
	v_cvt_pk_bf16_f32 v111, v106, v107
	global_store_dwordx4 v[112:113], v[108:111], off
	s_cbranch_vccnz .LBB0_129
	v_mov_b32_e32 v114, v103
	v_mov_b32_e32 v116, v99
	v_mov_b32_e32 v118, v144
	v_mov_b32_e32 v119, v144
	v_mov_b64_e32 v[104:105], v[194:195]
	v_mov_b64_e32 v[106:107], v[196:197]
	v_mov_b64_e32 v[108:109], v[198:199]
	v_mov_b64_e32 v[110:111], v[200:201]
	v_pk_mul_f32 v[120:121], v[100:101], v[104:105] op_sel:[1,1] op_sel_hi:[1,0]
	v_pk_mul_f32 v[114:115], v[114:115], v[106:107] op_sel:[0,1] op_sel_hi:[0,0]
	v_pk_mul_f32 v[122:123], v[96:97], v[108:109] op_sel:[1,1] op_sel_hi:[1,0]
	v_pk_mul_f32 v[116:117], v[116:117], v[110:111] op_sel:[0,1] op_sel_hi:[0,0]
	v_pk_fma_f32 v[124:125], v[100:101], v[104:105], v[120:121] op_sel_hi:[0,1,1] neg_lo:[0,0,1] neg_hi:[0,0,1]
	v_pk_fma_f32 v[100:101], v[100:101], v[104:105], v[120:121] op_sel_hi:[0,1,1]
	v_pk_fma_f32 v[104:105], v[102:103], v[106:107], v[114:115] op_sel_hi:[0,1,1] neg_lo:[0,0,1] neg_hi:[0,0,1]
	v_pk_fma_f32 v[102:103], v[102:103], v[106:107], v[114:115] op_sel_hi:[0,1,1]
	v_pk_fma_f32 v[106:107], v[96:97], v[108:109], v[122:123] op_sel_hi:[0,1,1] neg_lo:[0,0,1] neg_hi:[0,0,1]
	v_pk_fma_f32 v[96:97], v[96:97], v[108:109], v[122:123] op_sel_hi:[0,1,1]
	v_pk_fma_f32 v[108:109], v[98:99], v[110:111], v[116:117] op_sel_hi:[0,1,1] neg_lo:[0,0,1] neg_hi:[0,0,1]
	v_pk_fma_f32 v[98:99], v[98:99], v[110:111], v[116:117] op_sel_hi:[0,1,1]
	v_mov_b32_e32 v105, v103
	v_mov_b32_e32 v125, v101
	v_mov_b32_e32 v109, v99
	v_mov_b32_e32 v107, v97
	v_pk_mul_f32 v[102:103], v[118:119], v[104:105]
	v_pk_mul_f32 v[100:101], v[144:145], v[124:125]
	v_pk_mul_f32 v[98:99], v[118:119], v[108:109]
	v_pk_mul_f32 v[96:97], v[144:145], v[106:107]
; __device__ __forceinline__ unsigned cvt_pk_bf16(float lo, float hi) { unsigned r; asm volatile("v_cvt_pk_bf16_f32 %0, %1, %2" : "=v"(r) : "v"(lo), "v"(hi)); return r; }
;     __device__ __forceinline__ void operator()(const f32x4 (&acc)[2][2][4][2], const pg8::Unit& u, int wr, int wc, int fr, int fq) const {
;     ...
;         for (int ai = 0; ai < 2; ++ai)
; #pragma unroll
;             for (int m = 0; m < 4; ++m) {
;                 const int row = row0 + ai * 128 + m * 16;
;                 bf16_t* rowp = O + (size_t)row * INP + col0;
; #pragma unroll
;                 for (int bj = 0; bj < 2; ++bj) {
;                     f32x4 v0 = acc[ai][bj][m][0], v1 = acc[ai][bj][m][1];
;                     if (rot) {
;                         const int pos = row & (SEQ - 1), j0 = ((col0 + bj * 128) & 127) >> 1;
;                         const f32x4* t = (const f32x4*)(sc + ((size_t)pos * 64 + j0) * 2);
;                         const f32x4 t0 = t[0], t1 = t[1];
;                         f32x4 r0, r1;
;                         r0[0] = v0[0] * t0[0] - v0[1] * t0[1]; r0[1] = v0[0] * t0[1] + v0[1] * t0[0];
;                         r0[2] = v0[2] * t0[2] - v0[3] * t0[3]; r0[3] = v0[2] * t0[3] + v0[3] * t0[2];
;                         r1[0] = v1[0] * t1[0] - v1[1] * t1[1]; r1[1] = v1[0] * t1[1] + v1[1] * t1[0];
;                         r1[2] = v1[2] * t1[2] - v1[3] * t1[3]; r1[3] = v1[2] * t1[3] + v1[3] * t1[2];
;                         v0 = r0 * ksc; v1 = r1 * ksc;
;                     }
;                     u32x4 w; w.x = cvt_pk_bf16(v0[0], v0[1]); w.y = cvt_pk_bf16(v0[2], v0[3]); w.z = cvt_pk_bf16(v1[0], v1[1]); w.w = cvt_pk_bf16(v1[2], v1[3]);
;                     *(u32x4*)(rowp + bj * 128) = w;
.LBB0_129:
	v_cvt_pk_bf16_f32 v100, v100, v101
	v_cvt_pk_bf16_f32 v101, v102, v103
	s_nop 0
	v_cvt_pk_bf16_f32 v102, v96, v97
	v_or_b32_e32 v96, 32, v157
	v_lshlrev_b32_e32 v97, 7, v96
	v_and_or_b32 v97, v97, s56, v158
	v_cvt_pk_bf16_f32 v103, v98, v99
	s_and_b64 vcc, exec, s[10:11]
	v_lshlrev_b32_e32 v98, 2, v97
	global_store_dwordx4 v[112:113], v[100:103], off offset:256
	s_cbranch_vccnz .LBB0_131
	global_load_dwordx4 v[194:197], v223, s[24:25]
	global_load_dwordx4 v[198:201], v223, s[24:25] offset:16
	v_mov_b32_e32 v108, v95
	v_mov_b32_e32 v110, v91
	v_mov_b32_e32 v112, v144
	v_mov_b32_e32 v113, v144
	s_waitcnt vmcnt(10)
	v_mov_b64_e32 v[100:101], v[202:203]
	v_mov_b64_e32 v[102:103], v[204:205]
	v_mov_b64_e32 v[104:105], v[206:207]
	v_mov_b64_e32 v[106:107], v[208:209]
	v_pk_mul_f32 v[114:115], v[92:93], v[100:101] op_sel:[1,1] op_sel_hi:[1,0]
	v_pk_mul_f32 v[108:109], v[108:109], v[102:103] op_sel:[0,1] op_sel_hi:[0,0]
	v_pk_mul_f32 v[116:117], v[88:89], v[104:105] op_sel:[1,1] op_sel_hi:[1,0]
	v_pk_mul_f32 v[110:111], v[110:111], v[106:107] op_sel:[0,1] op_sel_hi:[0,0]
	v_pk_fma_f32 v[118:119], v[92:93], v[100:101], v[114:115] op_sel_hi:[0,1,1] neg_lo:[0,0,1] neg_hi:[0,0,1]
	v_pk_fma_f32 v[92:93], v[92:93], v[100:101], v[114:115] op_sel_hi:[0,1,1]
	v_pk_fma_f32 v[100:101], v[94:95], v[102:103], v[108:109] op_sel_hi:[0,1,1] neg_lo:[0,0,1] neg_hi:[0,0,1]
	v_pk_fma_f32 v[94:95], v[94:95], v[102:103], v[108:109] op_sel_hi:[0,1,1]
	v_pk_fma_f32 v[102:103], v[88:89], v[104:105], v[116:117] op_sel_hi:[0,1,1] neg_lo:[0,0,1] neg_hi:[0,0,1]
	v_pk_fma_f32 v[88:89], v[88:89], v[104:105], v[116:117] op_sel_hi:[0,1,1]
	v_pk_fma_f32 v[104:105], v[90:91], v[106:107], v[110:111] op_sel_hi:[0,1,1] neg_lo:[0,0,1] neg_hi:[0,0,1]
	v_pk_fma_f32 v[90:91], v[90:91], v[106:107], v[110:111] op_sel_hi:[0,1,1]
	v_mov_b32_e32 v101, v95
	v_mov_b32_e32 v119, v93
	v_mov_b32_e32 v105, v91
	v_mov_b32_e32 v103, v89
	v_pk_mul_f32 v[94:95], v[112:113], v[100:101]
	v_pk_mul_f32 v[92:93], v[144:145], v[118:119]
	v_pk_mul_f32 v[90:91], v[112:113], v[104:105]
	v_pk_mul_f32 v[88:89], v[144:145], v[102:103]
.LBB0_131:
	s_nop 0
	v_mov_b64_e32 v[100:101], s[22:23]
	v_mad_i64_i32 v[96:97], s[4:5], v96, s54, v[100:101]
	v_lshl_add_u64 v[96:97], v[146:147], 1, v[96:97]
	s_and_b64 vcc, exec, s[10:11]
	v_cvt_pk_bf16_f32 v92, v92, v93
	v_cvt_pk_bf16_f32 v93, v94, v95
	v_cvt_pk_bf16_f32 v94, v88, v89
	v_cvt_pk_bf16_f32 v95, v90, v91
	global_store_dwordx4 v[96:97], v[92:95], off
	s_cbranch_vccnz .LBB0_133
	v_mov_b32_e32 v98, v87
	v_mov_b32_e32 v100, v83
	v_mov_b32_e32 v102, v144
	v_mov_b32_e32 v103, v144
	v_mov_b64_e32 v[88:89], v[202:203]
	v_mov_b64_e32 v[90:91], v[204:205]
	v_mov_b64_e32 v[92:93], v[206:207]
	v_mov_b64_e32 v[94:95], v[208:209]
	v_pk_mul_f32 v[104:105], v[84:85], v[88:89] op_sel:[1,1] op_sel_hi:[1,0]
	v_pk_mul_f32 v[98:99], v[98:99], v[90:91] op_sel:[0,1] op_sel_hi:[0,0]
	v_pk_mul_f32 v[106:107], v[80:81], v[92:93] op_sel:[1,1] op_sel_hi:[1,0]
	v_pk_mul_f32 v[100:101], v[100:101], v[94:95] op_sel:[0,1] op_sel_hi:[0,0]
	v_pk_fma_f32 v[108:109], v[84:85], v[88:89], v[104:105] op_sel_hi:[0,1,1] neg_lo:[0,0,1] neg_hi:[0,0,1]
	v_pk_fma_f32 v[84:85], v[84:85], v[88:89], v[104:105] op_sel_hi:[0,1,1]
	v_pk_fma_f32 v[88:89], v[86:87], v[90:91], v[98:99] op_sel_hi:[0,1,1] neg_lo:[0,0,1] neg_hi:[0,0,1]
	v_pk_fma_f32 v[86:87], v[86:87], v[90:91], v[98:99] op_sel_hi:[0,1,1]
	v_pk_fma_f32 v[90:91], v[80:81], v[92:93], v[106:107] op_sel_hi:[0,1,1] neg_lo:[0,0,1] neg_hi:[0,0,1]
	v_pk_fma_f32 v[80:81], v[80:81], v[92:93], v[106:107] op_sel_hi:[0,1,1]
	v_pk_fma_f32 v[92:93], v[82:83], v[94:95], v[100:101] op_sel_hi:[0,1,1] neg_lo:[0,0,1] neg_hi:[0,0,1]
	v_pk_fma_f32 v[82:83], v[82:83], v[94:95], v[100:101] op_sel_hi:[0,1,1]
	v_mov_b32_e32 v89, v87
	v_mov_b32_e32 v109, v85
	v_mov_b32_e32 v93, v83
	v_mov_b32_e32 v91, v81
	v_pk_mul_f32 v[86:87], v[102:103], v[88:89]
	v_pk_mul_f32 v[84:85], v[144:145], v[108:109]
	v_pk_mul_f32 v[82:83], v[102:103], v[92:93]
	v_pk_mul_f32 v[80:81], v[144:145], v[90:91]
.LBB0_133:
	v_cvt_pk_bf16_f32 v84, v84, v85
	v_cvt_pk_bf16_f32 v85, v86, v87
	s_nop 0
	v_cvt_pk_bf16_f32 v86, v80, v81
	v_or_b32_e32 v80, 48, v157
	v_lshlrev_b32_e32 v81, 7, v80
	v_and_or_b32 v81, v81, s57, v158
	v_cvt_pk_bf16_f32 v87, v82, v83
	s_and_b64 vcc, exec, s[10:11]
	v_lshlrev_b32_e32 v82, 2, v81
	global_store_dwordx4 v[96:97], v[84:87], off offset:256
	s_cbranch_vccnz .LBB0_135
	global_load_dwordx4 v[202:205], v224, s[24:25]
	global_load_dwordx4 v[206:209], v224, s[24:25] offset:16
	v_mov_b32_e32 v92, v79
	v_mov_b32_e32 v94, v75
	v_mov_b32_e32 v96, v144
	v_mov_b32_e32 v97, v144
	s_waitcnt vmcnt(12)
	v_mov_b64_e32 v[84:85], v[210:211]
	v_mov_b64_e32 v[86:87], v[212:213]
	v_mov_b64_e32 v[88:89], v[214:215]
	v_mov_b64_e32 v[90:91], v[216:217]
	v_pk_mul_f32 v[98:99], v[76:77], v[84:85] op_sel:[1,1] op_sel_hi:[1,0]
	v_pk_mul_f32 v[92:93], v[92:93], v[86:87] op_sel:[0,1] op_sel_hi:[0,0]
	v_pk_mul_f32 v[100:101], v[72:73], v[88:89] op_sel:[1,1] op_sel_hi:[1,0]
	v_pk_mul_f32 v[94:95], v[94:95], v[90:91] op_sel:[0,1] op_sel_hi:[0,0]
	v_pk_fma_f32 v[102:103], v[76:77], v[84:85], v[98:99] op_sel_hi:[0,1,1] neg_lo:[0,0,1] neg_hi:[0,0,1]
	v_pk_fma_f32 v[76:77], v[76:77], v[84:85], v[98:99] op_sel_hi:[0,1,1]
	v_pk_fma_f32 v[84:85], v[78:79], v[86:87], v[92:93] op_sel_hi:[0,1,1] neg_lo:[0,0,1] neg_hi:[0,0,1]
	v_pk_fma_f32 v[78:79], v[78:79], v[86:87], v[92:93] op_sel_hi:[0,1,1]
	v_pk_fma_f32 v[86:87], v[72:73], v[88:89], v[100:101] op_sel_hi:[0,1,1] neg_lo:[0,0,1] neg_hi:[0,0,1]
	v_pk_fma_f32 v[72:73], v[72:73], v[88:89], v[100:101] op_sel_hi:[0,1,1]
	v_pk_fma_f32 v[88:89], v[74:75], v[90:91], v[94:95] op_sel_hi:[0,1,1] neg_lo:[0,0,1] neg_hi:[0,0,1]
	v_pk_fma_f32 v[74:75], v[74:75], v[90:91], v[94:95] op_sel_hi:[0,1,1]
	v_mov_b32_e32 v85, v79
	v_mov_b32_e32 v103, v77
	v_mov_b32_e32 v89, v75
	v_mov_b32_e32 v87, v73
	v_pk_mul_f32 v[78:79], v[96:97], v[84:85]
	v_pk_mul_f32 v[76:77], v[144:145], v[102:103]
	v_pk_mul_f32 v[74:75], v[96:97], v[88:89]
	v_pk_mul_f32 v[72:73], v[144:145], v[86:87]
; __device__ __forceinline__ unsigned cvt_pk_bf16(float lo, float hi) { unsigned r; asm volatile("v_cvt_pk_bf16_f32 %0, %1, %2" : "=v"(r) : "v"(lo), "v"(hi)); return r; }
;     __device__ __forceinline__ void operator()(const f32x4 (&acc)[2][2][4][2], const pg8::Unit& u, int wr, int wc, int fr, int fq) const {
;     ...
;         for (int ai = 0; ai < 2; ++ai)
; #pragma unroll
;             for (int m = 0; m < 4; ++m) {
;                 const int row = row0 + ai * 128 + m * 16;
;                 bf16_t* rowp = O + (size_t)row * INP + col0;
; #pragma unroll
;                 for (int bj = 0; bj < 2; ++bj) {
;                     f32x4 v0 = acc[ai][bj][m][0], v1 = acc[ai][bj][m][1];
;                     if (rot) {
;                         const int pos = row & (SEQ - 1), j0 = ((col0 + bj * 128) & 127) >> 1;
;                         const f32x4* t = (const f32x4*)(sc + ((size_t)pos * 64 + j0) * 2);
;                         const f32x4 t0 = t[0], t1 = t[1];
;                         f32x4 r0, r1;
;                         r0[0] = v0[0] * t0[0] - v0[1] * t0[1]; r0[1] = v0[0] * t0[1] + v0[1] * t0[0];
;                         r0[2] = v0[2] * t0[2] - v0[3] * t0[3]; r0[3] = v0[2] * t0[3] + v0[3] * t0[2];
;                         r1[0] = v1[0] * t1[0] - v1[1] * t1[1]; r1[1] = v1[0] * t1[1] + v1[1] * t1[0];
;                         r1[2] = v1[2] * t1[2] - v1[3] * t1[3]; r1[3] = v1[2] * t1[3] + v1[3] * t1[2];
;                         v0 = r0 * ksc; v1 = r1 * ksc;
;                     }
;                     u32x4 w; w.x = cvt_pk_bf16(v0[0], v0[1]); w.y = cvt_pk_bf16(v0[2], v0[3]); w.z = cvt_pk_bf16(v1[0], v1[1]); w.w = cvt_pk_bf16(v1[2], v1[3]);
;                     *(u32x4*)(rowp + bj * 128) = w;
.LBB0_135:
	s_nop 0
	v_mov_b64_e32 v[84:85], s[22:23]
	v_mad_i64_i32 v[80:81], s[4:5], v80, s54, v[84:85]
	v_lshl_add_u64 v[80:81], v[146:147], 1, v[80:81]
	s_and_b64 vcc, exec, s[10:11]
	v_cvt_pk_bf16_f32 v76, v76, v77
	v_cvt_pk_bf16_f32 v77, v78, v79
	v_cvt_pk_bf16_f32 v78, v72, v73
	v_cvt_pk_bf16_f32 v79, v74, v75
	global_store_dwordx4 v[80:81], v[76:79], off
	s_cbranch_vccnz .LBB0_137
	v_mov_b32_e32 v82, v71
	v_mov_b32_e32 v84, v67
	v_mov_b32_e32 v86, v144
	v_mov_b32_e32 v87, v144
	v_mov_b64_e32 v[72:73], v[210:211]
	v_mov_b64_e32 v[74:75], v[212:213]
	v_mov_b64_e32 v[76:77], v[214:215]
	v_mov_b64_e32 v[78:79], v[216:217]
	v_pk_mul_f32 v[88:89], v[68:69], v[72:73] op_sel:[1,1] op_sel_hi:[1,0]
	v_pk_mul_f32 v[82:83], v[82:83], v[74:75] op_sel:[0,1] op_sel_hi:[0,0]
	v_pk_mul_f32 v[90:91], v[64:65], v[76:77] op_sel:[1,1] op_sel_hi:[1,0]
	v_pk_mul_f32 v[84:85], v[84:85], v[78:79] op_sel:[0,1] op_sel_hi:[0,0]
	v_pk_fma_f32 v[92:93], v[68:69], v[72:73], v[88:89] op_sel_hi:[0,1,1] neg_lo:[0,0,1] neg_hi:[0,0,1]
	v_pk_fma_f32 v[68:69], v[68:69], v[72:73], v[88:89] op_sel_hi:[0,1,1]
	v_pk_fma_f32 v[72:73], v[70:71], v[74:75], v[82:83] op_sel_hi:[0,1,1] neg_lo:[0,0,1] neg_hi:[0,0,1]
	v_pk_fma_f32 v[70:71], v[70:71], v[74:75], v[82:83] op_sel_hi:[0,1,1]
	v_pk_fma_f32 v[74:75], v[64:65], v[76:77], v[90:91] op_sel_hi:[0,1,1] neg_lo:[0,0,1] neg_hi:[0,0,1]
	v_pk_fma_f32 v[64:65], v[64:65], v[76:77], v[90:91] op_sel_hi:[0,1,1]
	v_pk_fma_f32 v[76:77], v[66:67], v[78:79], v[84:85] op_sel_hi:[0,1,1] neg_lo:[0,0,1] neg_hi:[0,0,1]
	v_pk_fma_f32 v[66:67], v[66:67], v[78:79], v[84:85] op_sel_hi:[0,1,1]
	v_mov_b32_e32 v73, v71
	v_mov_b32_e32 v93, v69
	v_mov_b32_e32 v77, v67
	v_mov_b32_e32 v75, v65
	v_pk_mul_f32 v[70:71], v[86:87], v[72:73]
	v_pk_mul_f32 v[68:69], v[144:145], v[92:93]
	v_pk_mul_f32 v[66:67], v[86:87], v[76:77]
	v_pk_mul_f32 v[64:65], v[144:145], v[74:75]
.LBB0_137:
	v_cvt_pk_bf16_f32 v68, v68, v69
	v_cvt_pk_bf16_f32 v69, v70, v71
	s_nop 0
	v_cvt_pk_bf16_f32 v70, v64, v65
	v_add_u32_e32 v64, 0x80, v157
	v_lshlrev_b32_e32 v65, 7, v64
	v_and_or_b32 v65, v65, s49, v158
	v_cvt_pk_bf16_f32 v71, v66, v67
	s_and_b64 vcc, exec, s[10:11]
	v_lshlrev_b32_e32 v66, 2, v65
	global_store_dwordx4 v[80:81], v[68:71], off offset:256
	s_cbranch_vccnz .LBB0_139
	global_load_dwordx4 v[210:213], v225, s[24:25]
	global_load_dwordx4 v[214:217], v225, s[24:25] offset:16
	v_mov_b32_e32 v76, v63
	v_mov_b32_e32 v78, v59
	v_mov_b32_e32 v80, v144
	v_mov_b32_e32 v81, v144
	s_waitcnt vmcnt(12)
	v_mov_b64_e32 v[68:69], v[186:187]
	v_mov_b64_e32 v[70:71], v[188:189]
	v_mov_b64_e32 v[72:73], v[190:191]
	v_mov_b64_e32 v[74:75], v[192:193]
	v_pk_mul_f32 v[82:83], v[60:61], v[68:69] op_sel:[1,1] op_sel_hi:[1,0]
	v_pk_mul_f32 v[76:77], v[76:77], v[70:71] op_sel:[0,1] op_sel_hi:[0,0]
	v_pk_mul_f32 v[84:85], v[56:57], v[72:73] op_sel:[1,1] op_sel_hi:[1,0]
	v_pk_mul_f32 v[78:79], v[78:79], v[74:75] op_sel:[0,1] op_sel_hi:[0,0]
	v_pk_fma_f32 v[86:87], v[60:61], v[68:69], v[82:83] op_sel_hi:[0,1,1] neg_lo:[0,0,1] neg_hi:[0,0,1]
	v_pk_fma_f32 v[60:61], v[60:61], v[68:69], v[82:83] op_sel_hi:[0,1,1]
	v_pk_fma_f32 v[68:69], v[62:63], v[70:71], v[76:77] op_sel_hi:[0,1,1] neg_lo:[0,0,1] neg_hi:[0,0,1]
	v_pk_fma_f32 v[62:63], v[62:63], v[70:71], v[76:77] op_sel_hi:[0,1,1]
	v_pk_fma_f32 v[70:71], v[56:57], v[72:73], v[84:85] op_sel_hi:[0,1,1] neg_lo:[0,0,1] neg_hi:[0,0,1]
	v_pk_fma_f32 v[56:57], v[56:57], v[72:73], v[84:85] op_sel_hi:[0,1,1]
	v_pk_fma_f32 v[72:73], v[58:59], v[74:75], v[78:79] op_sel_hi:[0,1,1] neg_lo:[0,0,1] neg_hi:[0,0,1]
	v_pk_fma_f32 v[58:59], v[58:59], v[74:75], v[78:79] op_sel_hi:[0,1,1]
	v_mov_b32_e32 v69, v63
	v_mov_b32_e32 v87, v61
	v_mov_b32_e32 v73, v59
	v_mov_b32_e32 v71, v57
	v_pk_mul_f32 v[62:63], v[80:81], v[68:69]
	v_pk_mul_f32 v[60:61], v[144:145], v[86:87]
	v_pk_mul_f32 v[58:59], v[80:81], v[72:73]
	v_pk_mul_f32 v[56:57], v[144:145], v[70:71]
.LBB0_139:
	s_nop 0
	v_mov_b64_e32 v[68:69], s[22:23]
	v_mad_i64_i32 v[64:65], s[4:5], v64, s54, v[68:69]
	v_lshl_add_u64 v[64:65], v[146:147], 1, v[64:65]
	s_and_b64 vcc, exec, s[10:11]
	v_cvt_pk_bf16_f32 v60, v60, v61
	v_cvt_pk_bf16_f32 v61, v62, v63
	v_cvt_pk_bf16_f32 v62, v56, v57
	v_cvt_pk_bf16_f32 v63, v58, v59
	global_store_dwordx4 v[64:65], v[60:63], off
	s_cbranch_vccnz .LBB0_141
	v_mov_b32_e32 v66, v55
	v_mov_b32_e32 v68, v51
	v_mov_b32_e32 v70, v144
	v_mov_b32_e32 v71, v144
	v_mov_b64_e32 v[56:57], v[186:187]
	v_mov_b64_e32 v[58:59], v[188:189]
	v_mov_b64_e32 v[60:61], v[190:191]
	v_mov_b64_e32 v[62:63], v[192:193]
	v_pk_mul_f32 v[72:73], v[52:53], v[56:57] op_sel:[1,1] op_sel_hi:[1,0]
	v_pk_mul_f32 v[66:67], v[66:67], v[58:59] op_sel:[0,1] op_sel_hi:[0,0]
	v_pk_mul_f32 v[74:75], v[48:49], v[60:61] op_sel:[1,1] op_sel_hi:[1,0]
	v_pk_mul_f32 v[68:69], v[68:69], v[62:63] op_sel:[0,1] op_sel_hi:[0,0]
	v_pk_fma_f32 v[76:77], v[52:53], v[56:57], v[72:73] op_sel_hi:[0,1,1] neg_lo:[0,0,1] neg_hi:[0,0,1]
	v_pk_fma_f32 v[52:53], v[52:53], v[56:57], v[72:73] op_sel_hi:[0,1,1]
	v_pk_fma_f32 v[56:57], v[54:55], v[58:59], v[66:67] op_sel_hi:[0,1,1] neg_lo:[0,0,1] neg_hi:[0,0,1]
	v_pk_fma_f32 v[54:55], v[54:55], v[58:59], v[66:67] op_sel_hi:[0,1,1]
	v_pk_fma_f32 v[58:59], v[48:49], v[60:61], v[74:75] op_sel_hi:[0,1,1] neg_lo:[0,0,1] neg_hi:[0,0,1]
	v_pk_fma_f32 v[48:49], v[48:49], v[60:61], v[74:75] op_sel_hi:[0,1,1]
	v_pk_fma_f32 v[60:61], v[50:51], v[62:63], v[68:69] op_sel_hi:[0,1,1] neg_lo:[0,0,1] neg_hi:[0,0,1]
	v_pk_fma_f32 v[50:51], v[50:51], v[62:63], v[68:69] op_sel_hi:[0,1,1]
	v_mov_b32_e32 v57, v55
	v_mov_b32_e32 v77, v53
	v_mov_b32_e32 v61, v51
	v_mov_b32_e32 v59, v49
	v_pk_mul_f32 v[54:55], v[70:71], v[56:57]
	v_pk_mul_f32 v[52:53], v[144:145], v[76:77]
	v_pk_mul_f32 v[50:51], v[70:71], v[60:61]
	v_pk_mul_f32 v[48:49], v[144:145], v[58:59]
; __device__ __forceinline__ unsigned cvt_pk_bf16(float lo, float hi) { unsigned r; asm volatile("v_cvt_pk_bf16_f32 %0, %1, %2" : "=v"(r) : "v"(lo), "v"(hi)); return r; }
;     __device__ __forceinline__ void operator()(const f32x4 (&acc)[2][2][4][2], const pg8::Unit& u, int wr, int wc, int fr, int fq) const {
;     ...
;         for (int ai = 0; ai < 2; ++ai)
; #pragma unroll
;             for (int m = 0; m < 4; ++m) {
;                 const int row = row0 + ai * 128 + m * 16;
;                 bf16_t* rowp = O + (size_t)row * INP + col0;
; #pragma unroll
;                 for (int bj = 0; bj < 2; ++bj) {
;                     f32x4 v0 = acc[ai][bj][m][0], v1 = acc[ai][bj][m][1];
;                     if (rot) {
;                         const int pos = row & (SEQ - 1), j0 = ((col0 + bj * 128) & 127) >> 1;
;                         const f32x4* t = (const f32x4*)(sc + ((size_t)pos * 64 + j0) * 2);
;                         const f32x4 t0 = t[0], t1 = t[1];
;                         f32x4 r0, r1;
;                         r0[0] = v0[0] * t0[0] - v0[1] * t0[1]; r0[1] = v0[0] * t0[1] + v0[1] * t0[0];
;                         r0[2] = v0[2] * t0[2] - v0[3] * t0[3]; r0[3] = v0[2] * t0[3] + v0[3] * t0[2];
;                         r1[0] = v1[0] * t1[0] - v1[1] * t1[1]; r1[1] = v1[0] * t1[1] + v1[1] * t1[0];
;                         r1[2] = v1[2] * t1[2] - v1[3] * t1[3]; r1[3] = v1[2] * t1[3] + v1[3] * t1[2];
;                         v0 = r0 * ksc; v1 = r1 * ksc;
;                     }
;                     u32x4 w; w.x = cvt_pk_bf16(v0[0], v0[1]); w.y = cvt_pk_bf16(v0[2], v0[3]); w.z = cvt_pk_bf16(v1[0], v1[1]); w.w = cvt_pk_bf16(v1[2], v1[3]);
;                     *(u32x4*)(rowp + bj * 128) = w;
.LBB0_141:
	v_cvt_pk_bf16_f32 v52, v52, v53
	v_cvt_pk_bf16_f32 v53, v54, v55
	s_nop 0
	v_cvt_pk_bf16_f32 v54, v48, v49
	v_add_u32_e32 v48, 0x90, v157
	v_lshlrev_b32_e32 v49, 7, v48
	v_and_or_b32 v49, v49, s55, v158
	v_cvt_pk_bf16_f32 v55, v50, v51
	s_and_b64 vcc, exec, s[10:11]
	v_lshlrev_b32_e32 v50, 2, v49
	global_store_dwordx4 v[64:65], v[52:55], off offset:256
	s_cbranch_vccnz .LBB0_143
	v_mov_b32_e32 v60, v47
	v_mov_b32_e32 v62, v43
	v_mov_b32_e32 v64, v144
	v_mov_b32_e32 v65, v144
	s_waitcnt vmcnt(10)
	v_mov_b64_e32 v[52:53], v[194:195]
	v_mov_b64_e32 v[54:55], v[196:197]
	v_mov_b64_e32 v[56:57], v[198:199]
	v_mov_b64_e32 v[58:59], v[200:201]
	v_pk_mul_f32 v[66:67], v[44:45], v[52:53] op_sel:[1,1] op_sel_hi:[1,0]
	v_pk_mul_f32 v[60:61], v[60:61], v[54:55] op_sel:[0,1] op_sel_hi:[0,0]
	v_pk_mul_f32 v[68:69], v[40:41], v[56:57] op_sel:[1,1] op_sel_hi:[1,0]
	v_pk_mul_f32 v[62:63], v[62:63], v[58:59] op_sel:[0,1] op_sel_hi:[0,0]
	v_pk_fma_f32 v[70:71], v[44:45], v[52:53], v[66:67] op_sel_hi:[0,1,1] neg_lo:[0,0,1] neg_hi:[0,0,1]
	v_pk_fma_f32 v[44:45], v[44:45], v[52:53], v[66:67] op_sel_hi:[0,1,1]
	v_pk_fma_f32 v[52:53], v[46:47], v[54:55], v[60:61] op_sel_hi:[0,1,1] neg_lo:[0,0,1] neg_hi:[0,0,1]
	v_pk_fma_f32 v[46:47], v[46:47], v[54:55], v[60:61] op_sel_hi:[0,1,1]
	v_pk_fma_f32 v[54:55], v[40:41], v[56:57], v[68:69] op_sel_hi:[0,1,1] neg_lo:[0,0,1] neg_hi:[0,0,1]
	v_pk_fma_f32 v[40:41], v[40:41], v[56:57], v[68:69] op_sel_hi:[0,1,1]
	v_pk_fma_f32 v[56:57], v[42:43], v[58:59], v[62:63] op_sel_hi:[0,1,1] neg_lo:[0,0,1] neg_hi:[0,0,1]
	v_pk_fma_f32 v[42:43], v[42:43], v[58:59], v[62:63] op_sel_hi:[0,1,1]
	v_mov_b32_e32 v53, v47
	v_mov_b32_e32 v71, v45
	v_mov_b32_e32 v57, v43
	v_mov_b32_e32 v55, v41
	v_pk_mul_f32 v[46:47], v[64:65], v[52:53]
	v_pk_mul_f32 v[44:45], v[144:145], v[70:71]
	v_pk_mul_f32 v[42:43], v[64:65], v[56:57]
	v_pk_mul_f32 v[40:41], v[144:145], v[54:55]
.LBB0_143:
	s_nop 0
	v_mov_b64_e32 v[52:53], s[22:23]
	v_mad_i64_i32 v[48:49], s[4:5], v48, s54, v[52:53]
	v_lshl_add_u64 v[48:49], v[146:147], 1, v[48:49]
	s_and_b64 vcc, exec, s[10:11]
	v_cvt_pk_bf16_f32 v44, v44, v45
	v_cvt_pk_bf16_f32 v45, v46, v47
	v_cvt_pk_bf16_f32 v46, v40, v41
	v_cvt_pk_bf16_f32 v47, v42, v43
	global_store_dwordx4 v[48:49], v[44:47], off
	s_cbranch_vccnz .LBB0_145
	v_mov_b32_e32 v50, v39
	v_mov_b32_e32 v52, v35
	v_mov_b32_e32 v54, v144
	v_mov_b32_e32 v55, v144
	v_mov_b64_e32 v[40:41], v[194:195]
	v_mov_b64_e32 v[42:43], v[196:197]
	v_mov_b64_e32 v[44:45], v[198:199]
	v_mov_b64_e32 v[46:47], v[200:201]
	v_pk_mul_f32 v[56:57], v[36:37], v[40:41] op_sel:[1,1] op_sel_hi:[1,0]
	v_pk_mul_f32 v[50:51], v[50:51], v[42:43] op_sel:[0,1] op_sel_hi:[0,0]
	v_pk_mul_f32 v[58:59], v[32:33], v[44:45] op_sel:[1,1] op_sel_hi:[1,0]
	v_pk_mul_f32 v[52:53], v[52:53], v[46:47] op_sel:[0,1] op_sel_hi:[0,0]
	v_pk_fma_f32 v[60:61], v[36:37], v[40:41], v[56:57] op_sel_hi:[0,1,1] neg_lo:[0,0,1] neg_hi:[0,0,1]
	v_pk_fma_f32 v[36:37], v[36:37], v[40:41], v[56:57] op_sel_hi:[0,1,1]
	v_pk_fma_f32 v[40:41], v[38:39], v[42:43], v[50:51] op_sel_hi:[0,1,1] neg_lo:[0,0,1] neg_hi:[0,0,1]
	v_pk_fma_f32 v[38:39], v[38:39], v[42:43], v[50:51] op_sel_hi:[0,1,1]
	v_pk_fma_f32 v[42:43], v[32:33], v[44:45], v[58:59] op_sel_hi:[0,1,1] neg_lo:[0,0,1] neg_hi:[0,0,1]
	v_pk_fma_f32 v[32:33], v[32:33], v[44:45], v[58:59] op_sel_hi:[0,1,1]
	v_pk_fma_f32 v[44:45], v[34:35], v[46:47], v[52:53] op_sel_hi:[0,1,1] neg_lo:[0,0,1] neg_hi:[0,0,1]
	v_pk_fma_f32 v[34:35], v[34:35], v[46:47], v[52:53] op_sel_hi:[0,1,1]
	v_mov_b32_e32 v41, v39
	v_mov_b32_e32 v61, v37
	v_mov_b32_e32 v45, v35
	v_mov_b32_e32 v43, v33
	v_pk_mul_f32 v[38:39], v[54:55], v[40:41]
	v_pk_mul_f32 v[36:37], v[144:145], v[60:61]
	v_pk_mul_f32 v[34:35], v[54:55], v[44:45]
	v_pk_mul_f32 v[32:33], v[144:145], v[42:43]
.LBB0_145:
	v_cvt_pk_bf16_f32 v36, v36, v37
	v_cvt_pk_bf16_f32 v37, v38, v39
	s_nop 0
	v_cvt_pk_bf16_f32 v38, v32, v33
	v_add_u32_e32 v32, 0xa0, v157
	v_lshlrev_b32_e32 v33, 7, v32
	v_and_or_b32 v33, v33, s56, v158
	v_cvt_pk_bf16_f32 v39, v34, v35
	s_and_b64 vcc, exec, s[10:11]
	v_lshlrev_b32_e32 v34, 2, v33
	global_store_dwordx4 v[48:49], v[36:39], off offset:256
	s_cbranch_vccnz .LBB0_147
	v_mov_b32_e32 v44, v31
	v_mov_b32_e32 v46, v27
	v_mov_b32_e32 v48, v144
	v_mov_b32_e32 v49, v144
	s_waitcnt vmcnt(8)
	v_mov_b64_e32 v[36:37], v[202:203]
	v_mov_b64_e32 v[38:39], v[204:205]
	v_mov_b64_e32 v[40:41], v[206:207]
	v_mov_b64_e32 v[42:43], v[208:209]
	v_pk_mul_f32 v[50:51], v[28:29], v[36:37] op_sel:[1,1] op_sel_hi:[1,0]
	v_pk_mul_f32 v[44:45], v[44:45], v[38:39] op_sel:[0,1] op_sel_hi:[0,0]
	v_pk_mul_f32 v[52:53], v[24:25], v[40:41] op_sel:[1,1] op_sel_hi:[1,0]
	v_pk_mul_f32 v[46:47], v[46:47], v[42:43] op_sel:[0,1] op_sel_hi:[0,0]
	v_pk_fma_f32 v[54:55], v[28:29], v[36:37], v[50:51] op_sel_hi:[0,1,1] neg_lo:[0,0,1] neg_hi:[0,0,1]
	v_pk_fma_f32 v[28:29], v[28:29], v[36:37], v[50:51] op_sel_hi:[0,1,1]
	v_pk_fma_f32 v[36:37], v[30:31], v[38:39], v[44:45] op_sel_hi:[0,1,1] neg_lo:[0,0,1] neg_hi:[0,0,1]
	v_pk_fma_f32 v[30:31], v[30:31], v[38:39], v[44:45] op_sel_hi:[0,1,1]
	v_pk_fma_f32 v[38:39], v[24:25], v[40:41], v[52:53] op_sel_hi:[0,1,1] neg_lo:[0,0,1] neg_hi:[0,0,1]
	v_pk_fma_f32 v[24:25], v[24:25], v[40:41], v[52:53] op_sel_hi:[0,1,1]
	v_pk_fma_f32 v[40:41], v[26:27], v[42:43], v[46:47] op_sel_hi:[0,1,1] neg_lo:[0,0,1] neg_hi:[0,0,1]
	v_pk_fma_f32 v[26:27], v[26:27], v[42:43], v[46:47] op_sel_hi:[0,1,1]
	v_mov_b32_e32 v37, v31
	v_mov_b32_e32 v55, v29
	v_mov_b32_e32 v41, v27
	v_mov_b32_e32 v39, v25
	v_pk_mul_f32 v[30:31], v[48:49], v[36:37]
	v_pk_mul_f32 v[28:29], v[144:145], v[54:55]
	v_pk_mul_f32 v[26:27], v[48:49], v[40:41]
	v_pk_mul_f32 v[24:25], v[144:145], v[38:39]
; __device__ __forceinline__ unsigned cvt_pk_bf16(float lo, float hi) { unsigned r; asm volatile("v_cvt_pk_bf16_f32 %0, %1, %2" : "=v"(r) : "v"(lo), "v"(hi)); return r; }
;     __device__ __forceinline__ void operator()(const f32x4 (&acc)[2][2][4][2], const pg8::Unit& u, int wr, int wc, int fr, int fq) const {
;     ...
;         for (int ai = 0; ai < 2; ++ai)
; #pragma unroll
;             for (int m = 0; m < 4; ++m) {
;                 const int row = row0 + ai * 128 + m * 16;
;                 bf16_t* rowp = O + (size_t)row * INP + col0;
; #pragma unroll
;                 for (int bj = 0; bj < 2; ++bj) {
;                     f32x4 v0 = acc[ai][bj][m][0], v1 = acc[ai][bj][m][1];
;                     if (rot) {
;                         const int pos = row & (SEQ - 1), j0 = ((col0 + bj * 128) & 127) >> 1;
;                         const f32x4* t = (const f32x4*)(sc + ((size_t)pos * 64 + j0) * 2);
;                         const f32x4 t0 = t[0], t1 = t[1];
;                         f32x4 r0, r1;
;                         r0[0] = v0[0] * t0[0] - v0[1] * t0[1]; r0[1] = v0[0] * t0[1] + v0[1] * t0[0];
;                         r0[2] = v0[2] * t0[2] - v0[3] * t0[3]; r0[3] = v0[2] * t0[3] + v0[3] * t0[2];
;                         r1[0] = v1[0] * t1[0] - v1[1] * t1[1]; r1[1] = v1[0] * t1[1] + v1[1] * t1[0];
;                         r1[2] = v1[2] * t1[2] - v1[3] * t1[3]; r1[3] = v1[2] * t1[3] + v1[3] * t1[2];
;                         v0 = r0 * ksc; v1 = r1 * ksc;
;                     }
;                     u32x4 w; w.x = cvt_pk_bf16(v0[0], v0[1]); w.y = cvt_pk_bf16(v0[2], v0[3]); w.z = cvt_pk_bf16(v1[0], v1[1]); w.w = cvt_pk_bf16(v1[2], v1[3]);
;                     *(u32x4*)(rowp + bj * 128) = w;
.LBB0_147:
	s_nop 0
	v_mov_b64_e32 v[36:37], s[22:23]
	v_mad_i64_i32 v[32:33], s[4:5], v32, s54, v[36:37]
	v_lshl_add_u64 v[32:33], v[146:147], 1, v[32:33]
	s_and_b64 vcc, exec, s[10:11]
	v_cvt_pk_bf16_f32 v28, v28, v29
	v_cvt_pk_bf16_f32 v29, v30, v31
	v_cvt_pk_bf16_f32 v30, v24, v25
	v_cvt_pk_bf16_f32 v31, v26, v27
	global_store_dwordx4 v[32:33], v[28:31], off
	s_cbranch_vccnz .LBB0_149
	v_mov_b32_e32 v34, v23
	v_mov_b32_e32 v36, v19
	v_mov_b32_e32 v38, v144
	v_mov_b32_e32 v39, v144
	v_mov_b64_e32 v[24:25], v[202:203]
	v_mov_b64_e32 v[26:27], v[204:205]
	v_mov_b64_e32 v[28:29], v[206:207]
	v_mov_b64_e32 v[30:31], v[208:209]
	v_pk_mul_f32 v[40:41], v[20:21], v[24:25] op_sel:[1,1] op_sel_hi:[1,0]
	v_pk_mul_f32 v[34:35], v[34:35], v[26:27] op_sel:[0,1] op_sel_hi:[0,0]
	v_pk_mul_f32 v[42:43], v[16:17], v[28:29] op_sel:[1,1] op_sel_hi:[1,0]
	v_pk_mul_f32 v[36:37], v[36:37], v[30:31] op_sel:[0,1] op_sel_hi:[0,0]
	v_pk_fma_f32 v[44:45], v[20:21], v[24:25], v[40:41] op_sel_hi:[0,1,1] neg_lo:[0,0,1] neg_hi:[0,0,1]
	v_pk_fma_f32 v[20:21], v[20:21], v[24:25], v[40:41] op_sel_hi:[0,1,1]
	v_pk_fma_f32 v[24:25], v[22:23], v[26:27], v[34:35] op_sel_hi:[0,1,1] neg_lo:[0,0,1] neg_hi:[0,0,1]
	v_pk_fma_f32 v[22:23], v[22:23], v[26:27], v[34:35] op_sel_hi:[0,1,1]
	v_pk_fma_f32 v[26:27], v[16:17], v[28:29], v[42:43] op_sel_hi:[0,1,1] neg_lo:[0,0,1] neg_hi:[0,0,1]
	v_pk_fma_f32 v[16:17], v[16:17], v[28:29], v[42:43] op_sel_hi:[0,1,1]
	v_pk_fma_f32 v[28:29], v[18:19], v[30:31], v[36:37] op_sel_hi:[0,1,1] neg_lo:[0,0,1] neg_hi:[0,0,1]
	v_pk_fma_f32 v[18:19], v[18:19], v[30:31], v[36:37] op_sel_hi:[0,1,1]
	v_mov_b32_e32 v25, v23
	v_mov_b32_e32 v45, v21
	v_mov_b32_e32 v29, v19
	v_mov_b32_e32 v27, v17
	v_pk_mul_f32 v[22:23], v[38:39], v[24:25]
	v_pk_mul_f32 v[20:21], v[144:145], v[44:45]
	v_pk_mul_f32 v[18:19], v[38:39], v[28:29]
	v_pk_mul_f32 v[16:17], v[144:145], v[26:27]
.LBB0_149:
	v_cvt_pk_bf16_f32 v20, v20, v21
	v_cvt_pk_bf16_f32 v21, v22, v23
	s_nop 0
	v_cvt_pk_bf16_f32 v22, v16, v17
	v_add_u32_e32 v16, 0xb0, v157
	v_lshlrev_b32_e32 v17, 7, v16
	v_and_or_b32 v17, v17, s57, v158
	v_cvt_pk_bf16_f32 v23, v18, v19
	s_and_b64 vcc, exec, s[10:11]
	v_lshlrev_b32_e32 v18, 2, v17
	global_store_dwordx4 v[32:33], v[20:23], off offset:256
	s_cbranch_vccnz .LBB0_151
	v_mov_b32_e32 v28, v15
	v_mov_b32_e32 v30, v11
	v_mov_b32_e32 v32, v144
	v_mov_b32_e32 v33, v144
	s_waitcnt vmcnt(6)
	v_mov_b64_e32 v[20:21], v[210:211]
	v_mov_b64_e32 v[22:23], v[212:213]
	v_mov_b64_e32 v[24:25], v[214:215]
	v_mov_b64_e32 v[26:27], v[216:217]
	v_pk_mul_f32 v[34:35], v[12:13], v[20:21] op_sel:[1,1] op_sel_hi:[1,0]
	v_pk_mul_f32 v[28:29], v[28:29], v[22:23] op_sel:[0,1] op_sel_hi:[0,0]
	v_pk_mul_f32 v[36:37], v[8:9], v[24:25] op_sel:[1,1] op_sel_hi:[1,0]
	v_pk_mul_f32 v[30:31], v[30:31], v[26:27] op_sel:[0,1] op_sel_hi:[0,0]
	v_pk_fma_f32 v[38:39], v[12:13], v[20:21], v[34:35] op_sel_hi:[0,1,1] neg_lo:[0,0,1] neg_hi:[0,0,1]
	v_pk_fma_f32 v[12:13], v[12:13], v[20:21], v[34:35] op_sel_hi:[0,1,1]
	v_pk_fma_f32 v[20:21], v[14:15], v[22:23], v[28:29] op_sel_hi:[0,1,1] neg_lo:[0,0,1] neg_hi:[0,0,1]
	v_pk_fma_f32 v[14:15], v[14:15], v[22:23], v[28:29] op_sel_hi:[0,1,1]
	v_pk_fma_f32 v[22:23], v[8:9], v[24:25], v[36:37] op_sel_hi:[0,1,1] neg_lo:[0,0,1] neg_hi:[0,0,1]
	v_pk_fma_f32 v[8:9], v[8:9], v[24:25], v[36:37] op_sel_hi:[0,1,1]
	v_pk_fma_f32 v[24:25], v[10:11], v[26:27], v[30:31] op_sel_hi:[0,1,1] neg_lo:[0,0,1] neg_hi:[0,0,1]
	v_pk_fma_f32 v[10:11], v[10:11], v[26:27], v[30:31] op_sel_hi:[0,1,1]
	v_mov_b32_e32 v21, v15
	v_mov_b32_e32 v39, v13
	v_mov_b32_e32 v25, v11
	v_mov_b32_e32 v23, v9
	v_pk_mul_f32 v[14:15], v[32:33], v[20:21]
	v_pk_mul_f32 v[12:13], v[144:145], v[38:39]
	v_pk_mul_f32 v[10:11], v[32:33], v[24:25]
	v_pk_mul_f32 v[8:9], v[144:145], v[22:23]
.LBB0_151:
	s_nop 0
	v_mov_b64_e32 v[20:21], s[22:23]
	v_mad_i64_i32 v[16:17], s[4:5], v16, s54, v[20:21]
	v_lshl_add_u64 v[16:17], v[146:147], 1, v[16:17]
	s_and_b64 vcc, exec, s[10:11]
	v_cvt_pk_bf16_f32 v12, v12, v13
	v_cvt_pk_bf16_f32 v13, v14, v15
	v_cvt_pk_bf16_f32 v14, v8, v9
	v_cvt_pk_bf16_f32 v15, v10, v11
	global_store_dwordx4 v[16:17], v[12:15], off
	s_cbranch_vccnz .LBB0_116
	v_mov_b32_e32 v18, v7
	v_mov_b32_e32 v20, v3
	v_mov_b32_e32 v22, v144
	v_mov_b32_e32 v23, v144
	v_mov_b64_e32 v[8:9], v[210:211]
	v_mov_b64_e32 v[10:11], v[212:213]
	v_mov_b64_e32 v[12:13], v[214:215]
	v_mov_b64_e32 v[14:15], v[216:217]
	v_pk_mul_f32 v[24:25], v[4:5], v[8:9] op_sel:[1,1] op_sel_hi:[1,0]
	v_pk_mul_f32 v[18:19], v[18:19], v[10:11] op_sel:[0,1] op_sel_hi:[0,0]
	v_pk_mul_f32 v[26:27], v[0:1], v[12:13] op_sel:[1,1] op_sel_hi:[1,0]
	v_pk_mul_f32 v[20:21], v[20:21], v[14:15] op_sel:[0,1] op_sel_hi:[0,0]
	v_pk_fma_f32 v[28:29], v[4:5], v[8:9], v[24:25] op_sel_hi:[0,1,1] neg_lo:[0,0,1] neg_hi:[0,0,1]
	v_pk_fma_f32 v[4:5], v[4:5], v[8:9], v[24:25] op_sel_hi:[0,1,1]
	v_pk_fma_f32 v[8:9], v[6:7], v[10:11], v[18:19] op_sel_hi:[0,1,1] neg_lo:[0,0,1] neg_hi:[0,0,1]
	v_pk_fma_f32 v[6:7], v[6:7], v[10:11], v[18:19] op_sel_hi:[0,1,1]
	v_pk_fma_f32 v[10:11], v[0:1], v[12:13], v[26:27] op_sel_hi:[0,1,1] neg_lo:[0,0,1] neg_hi:[0,0,1]
	v_pk_fma_f32 v[0:1], v[0:1], v[12:13], v[26:27] op_sel_hi:[0,1,1]
	v_pk_fma_f32 v[12:13], v[2:3], v[14:15], v[20:21] op_sel_hi:[0,1,1] neg_lo:[0,0,1] neg_hi:[0,0,1]
	v_pk_fma_f32 v[2:3], v[2:3], v[14:15], v[20:21] op_sel_hi:[0,1,1]
	v_mov_b32_e32 v9, v7
	v_mov_b32_e32 v29, v5
	v_mov_b32_e32 v13, v3
	v_mov_b32_e32 v11, v1
	v_pk_mul_f32 v[6:7], v[22:23], v[8:9]
	v_pk_mul_f32 v[4:5], v[144:145], v[28:29]
	v_pk_mul_f32 v[2:3], v[22:23], v[12:13]
	v_pk_mul_f32 v[0:1], v[144:145], v[10:11]
	s_branch .LBB0_116
